# adds N2: all 16 row/cv loads of a q-iteration hoisted to its top (one memory round trip instead of ten serial ones)
# speedup vs baseline: 1.0018x; 1.0006x over previous
; __device__ __forceinline__ unsigned pk2(float lo, float hi) { return pg8::cvt_pk_bf16(lo, hi); }
; __device__ __forceinline__ float blo(unsigned w) { return __uint_as_float(w << 16); }
; __device__ __forceinline__ float bhi(unsigned w) { return __uint_as_float(w & 0xffff0000u); }
; __device__ __forceinline__ void n2_phase(unsigned char* ws, int layer, int gw, int NGW, int lane) {
;     ...
; #pragma unroll
;             for (int rr = 0; rr < 4; ++rr) {
;                 const v4u cv = *(const v4u*)(proj + (size_t)(r0 + rr) * NP + PC_SCC + c);
;                 float a[8];
; #pragma unroll
;                 for (int j = 0; j < 8; ++j) a[j] = wk[0][j] * pr[rr][j] + wk[1][j] * pr[rr + 1][j] + wk[2][j] * pr[rr + 2][j];
;                 v4u o; o.x = pk2(blo(cv.x) * a[0], bhi(cv.x) * a[1]); o.y = pk2(blo(cv.y) * a[2], bhi(cv.y) * a[3]); o.z = pk2(blo(cv.z) * a[4], bhi(cv.z) * a[5]); o.w = pk2(blo(cv.w) * a[6], bhi(cv.w) * a[7]);
;                 *(v4u*)(ysc + (size_t)(r0 + rr) * D + c) = o;
;             }
.LBB0_756:
	v_add_co_u32_e32 v104, vcc, s3, v104
	s_waitcnt vmcnt(3)
	v_pk_mul_f32 v[114:115], v[18:19], v[72:73]
	v_addc_co_u32_e32 v105, vcc, 0, v105, vcc
	v_mov_b32_e32 v110, v168
	v_mov_b32_e32 v111, v169
	v_mov_b32_e32 v112, v170
	v_mov_b32_e32 v113, v171
	v_pk_mul_f32 v[104:105], v[16:17], v[78:79]
	v_pk_fma_f32 v[86:87], v[14:15], v[86:87], v[114:115]
	v_pk_fma_f32 v[84:85], v[12:13], v[84:85], v[104:105]
	s_waitcnt vmcnt(2)
	v_pk_fma_f32 v[86:87], v[22:23], v[62:63], v[86:87]
	v_pk_fma_f32 v[84:85], v[20:21], v[66:67], v[84:85]
	v_pk_mul_f32 v[116:117], v[4:5], v[68:69]
	v_pk_mul_f32 v[118:119], v[6:7], v[56:57]
	s_mov_b64 s[24:25], 0x800
	v_lshl_add_u64 v[48:49], v[48:49], 0, s[24:25]
	v_lshl_add_u64 v[36:37], v[36:37], 0, s[62:63]
	v_lshl_add_u64 v[38:39], v[38:39], 0, s[62:63]
	v_lshl_add_u64 v[40:41], v[40:41], 0, s[62:63]
	v_lshl_add_u64 v[42:43], v[42:43], 0, s[62:63]
	v_lshl_add_u64 v[44:45], v[44:45], 0, s[62:63]
	v_lshl_add_u64 v[46:47], v[46:47], 0, s[62:63]
	s_waitcnt vmcnt(0)
	v_lshlrev_b32_e32 v104, 16, v110
	v_and_b32_e32 v105, 0xffff0000, v110
	v_pk_mul_f32 v[84:85], v[84:85], v[104:105]
	v_lshlrev_b32_e32 v104, 16, v111
	v_and_b32_e32 v105, 0xffff0000, v111
	v_pk_mul_f32 v[86:87], v[86:87], v[104:105]
	v_cvt_pk_bf16_f32 v84, v84, v85
	v_cvt_pk_bf16_f32 v85, v86, v87
	v_pk_fma_f32 v[86:87], v[0:1], v[88:89], v[116:117]
	v_lshlrev_b32_e32 v88, 16, v112
	v_pk_fma_f32 v[86:87], v[8:9], v[60:61], v[86:87]
	v_and_b32_e32 v89, 0xffff0000, v112
	v_pk_mul_f32 v[86:87], v[86:87], v[88:89]
	v_pk_fma_f32 v[88:89], v[2:3], v[90:91], v[118:119]
	v_lshlrev_b32_e32 v90, 16, v113
	v_pk_fma_f32 v[88:89], v[10:11], v[64:65], v[88:89]
	v_and_b32_e32 v91, 0xffff0000, v113
	v_pk_mul_f32 v[88:89], v[88:89], v[90:91]
	v_cvt_pk_bf16_f32 v86, v86, v87
	v_cvt_pk_bf16_f32 v87, v88, v89
	v_lshl_add_u64 v[88:89], v[34:35], 0, s[0:1]
	global_store_dwordx4 v[88:89], v[84:87], off
	v_pk_mul_f32 v[88:89], v[16:17], v[66:67]
	s_add_u32 s0, s0, 0x400
	v_add_co_u32_e32 v84, vcc, s3, v102
	v_pk_fma_f32 v[78:79], v[12:13], v[78:79], v[88:89]
	s_nop 0
	v_addc_co_u32_e32 v85, vcc, 0, v103, vcc
	v_mov_b32_e32 v84, v172
	v_mov_b32_e32 v85, v173
	v_mov_b32_e32 v86, v174
	v_mov_b32_e32 v87, v175
	v_pk_fma_f32 v[78:79], v[20:21], v[58:59], v[78:79]
	s_addc_u32 s1, s1, 0
	s_waitcnt vmcnt(0)
	v_lshlrev_b32_e32 v88, 16, v84
	v_and_b32_e32 v89, 0xffff0000, v84
	v_pk_mul_f32 v[78:79], v[78:79], v[88:89]
	s_nop 0
	v_cvt_pk_bf16_f32 v84, v78, v79
	v_pk_mul_f32 v[78:79], v[18:19], v[62:63]
	s_nop 0
	v_pk_fma_f32 v[72:73], v[14:15], v[72:73], v[78:79]
	v_lshlrev_b32_e32 v78, 16, v85
	v_pk_fma_f32 v[72:73], v[22:23], v[54:55], v[72:73]
	v_and_b32_e32 v79, 0xffff0000, v85
	v_pk_mul_f32 v[72:73], v[72:73], v[78:79]
	s_nop 0
	v_cvt_pk_bf16_f32 v85, v72, v73
	v_pk_mul_f32 v[72:73], v[4:5], v[60:61]
	s_nop 0
	v_pk_fma_f32 v[68:69], v[0:1], v[68:69], v[72:73]
	v_lshlrev_b32_e32 v72, 16, v86
	v_pk_fma_f32 v[68:69], v[8:9], v[52:53], v[68:69]
	v_and_b32_e32 v73, 0xffff0000, v86
	v_pk_mul_f32 v[68:69], v[68:69], v[72:73]
	s_nop 0
	v_cvt_pk_bf16_f32 v86, v68, v69
	v_pk_mul_f32 v[68:69], v[6:7], v[64:65]
	s_nop 0
	v_pk_fma_f32 v[56:57], v[2:3], v[56:57], v[68:69]
	v_lshlrev_b32_e32 v68, 16, v87
	v_pk_fma_f32 v[56:57], v[10:11], v[50:51], v[56:57]
	v_and_b32_e32 v69, 0xffff0000, v87
	v_pk_mul_f32 v[56:57], v[56:57], v[68:69]
	s_nop 0
	v_cvt_pk_bf16_f32 v87, v56, v57
	v_lshl_add_u64 v[56:57], v[34:35], 0, s[16:17]
	global_store_dwordx4 v[56:57], v[84:87], off
	v_add_co_u32_e32 v56, vcc, s3, v100
	s_add_u32 s16, s16, 0x400
	s_nop 0
	v_addc_co_u32_e32 v57, vcc, 0, v101, vcc
	v_mov_b32_e32 v84, v176
	v_mov_b32_e32 v85, v177
	v_mov_b32_e32 v86, v178
	v_mov_b32_e32 v87, v179
	v_pk_mul_f32 v[56:57], v[16:17], v[58:59]
	v_pk_mul_f32 v[16:17], v[16:17], v[82:83]
	v_pk_fma_f32 v[56:57], v[12:13], v[66:67], v[56:57]
	v_pk_fma_f32 v[12:13], v[12:13], v[58:59], v[16:17]
	v_pk_fma_f32 v[56:57], v[20:21], v[82:83], v[56:57]
	v_pk_fma_f32 v[12:13], v[20:21], v[98:99], v[12:13]
	s_addc_u32 s17, s17, 0
	s_waitcnt vmcnt(0)
	v_lshlrev_b32_e32 v66, 16, v84
	v_and_b32_e32 v67, 0xffff0000, v84
	v_pk_mul_f32 v[56:57], v[56:57], v[66:67]
	s_nop 0
	v_cvt_pk_bf16_f32 v66, v56, v57
	v_pk_mul_f32 v[56:57], v[18:19], v[54:55]
	s_nop 0
	v_pk_fma_f32 v[56:57], v[14:15], v[62:63], v[56:57]
	v_lshlrev_b32_e32 v62, 16, v85
	v_pk_fma_f32 v[56:57], v[22:23], v[74:75], v[56:57]
	v_and_b32_e32 v63, 0xffff0000, v85
	v_pk_mul_f32 v[56:57], v[56:57], v[62:63]
	s_nop 0
	v_cvt_pk_bf16_f32 v67, v56, v57
	v_pk_mul_f32 v[56:57], v[4:5], v[52:53]
	v_pk_mul_f32 v[4:5], v[4:5], v[70:71]
	v_pk_fma_f32 v[56:57], v[0:1], v[60:61], v[56:57]
	v_lshlrev_b32_e32 v60, 16, v86
	v_pk_fma_f32 v[56:57], v[8:9], v[70:71], v[56:57]
	v_and_b32_e32 v61, 0xffff0000, v86
	v_pk_mul_f32 v[56:57], v[56:57], v[60:61]
	v_lshlrev_b32_e32 v60, 16, v87
	v_cvt_pk_bf16_f32 v68, v56, v57
	v_pk_mul_f32 v[56:57], v[6:7], v[50:51]
	v_and_b32_e32 v61, 0xffff0000, v87
	v_pk_fma_f32 v[56:57], v[2:3], v[64:65], v[56:57]
	v_pk_fma_f32 v[0:1], v[0:1], v[52:53], v[4:5]
	v_pk_fma_f32 v[56:57], v[10:11], v[76:77], v[56:57]
	v_pk_fma_f32 v[0:1], v[8:9], v[92:93], v[0:1]
	v_pk_mul_f32 v[56:57], v[56:57], v[60:61]
	s_nop 0
	v_cvt_pk_bf16_f32 v69, v56, v57
	v_lshl_add_u64 v[56:57], v[34:35], 0, s[22:23]
	global_store_dwordx4 v[56:57], v[66:69], off
	v_add_co_u32_e32 v56, vcc, s3, v94
	s_add_u32 s22, s22, 0x400
	s_nop 0
	v_addc_co_u32_e32 v57, vcc, 0, v95, vcc
	v_mov_b32_e32 v60, v180
	v_mov_b32_e32 v61, v181
	v_mov_b32_e32 v62, v182
	v_mov_b32_e32 v63, v183
	s_addc_u32 s23, s23, 0
	s_waitcnt vmcnt(0)
	v_lshlrev_b32_e32 v16, 16, v60
	v_and_b32_e32 v17, 0xffff0000, v60
	v_pk_mul_f32 v[12:13], v[12:13], v[16:17]
	v_pk_mul_f32 v[16:17], v[18:19], v[74:75]
	v_lshlrev_b32_e32 v4, 16, v62
	v_pk_fma_f32 v[14:15], v[14:15], v[54:55], v[16:17]
	v_lshlrev_b32_e32 v16, 16, v61
	v_pk_fma_f32 v[14:15], v[22:23], v[96:97], v[14:15]
	v_and_b32_e32 v17, 0xffff0000, v61
	v_and_b32_e32 v5, 0xffff0000, v62
	v_pk_mul_f32 v[14:15], v[14:15], v[16:17]
	v_pk_mul_f32 v[0:1], v[0:1], v[4:5]
	v_cvt_pk_bf16_f32 v12, v12, v13
	v_cvt_pk_bf16_f32 v13, v14, v15
	v_cvt_pk_bf16_f32 v14, v0, v1
	v_pk_mul_f32 v[0:1], v[6:7], v[76:77]
	s_nop 0
	v_pk_fma_f32 v[0:1], v[2:3], v[50:51], v[0:1]
	v_lshlrev_b32_e32 v2, 16, v63
	v_pk_fma_f32 v[0:1], v[10:11], v[80:81], v[0:1]
	v_and_b32_e32 v3, 0xffff0000, v63
	v_pk_mul_f32 v[0:1], v[0:1], v[2:3]
	s_nop 0
	v_cvt_pk_bf16_f32 v15, v0, v1
	v_lshl_add_u64 v[0:1], v[34:35], 0, s[26:27]
	s_add_u32 s26, s26, 0x400
	s_addc_u32 s27, s27, 0
	s_add_i32 s9, s9, -1
	s_cmp_eq_u32 s9, 0
	global_store_dwordx4 v[0:1], v[12:15], off
	s_cbranch_scc1 .LBB0_752
; __device__ __forceinline__ float blo(unsigned w) { return __uint_as_float(w << 16); }
; __device__ __forceinline__ float bhi(unsigned w) { return __uint_as_float(w & 0xffff0000u); }
; __device__ __forceinline__ void n2_phase(unsigned char* ws, int layer, int gw, int NGW, int lane) {
;     ...
;         for (int q = 0; q < 4; ++q) {
;             const int c = q * 512 + lane * 8;
;             float wk[3][8];
; #pragma unroll
;             for (int k = 0; k < 3; ++k) { const f32x4 w0 = *(const f32x4*)(scw + k * D + c), w1 = *(const f32x4*)(scw + k * D + c + 4);
;                 wk[k][0] = w0[0]; wk[k][1] = w0[1]; wk[k][2] = w0[2]; wk[k][3] = w0[3]; wk[k][4] = w1[0]; wk[k][5] = w1[1]; wk[k][6] = w1[2]; wk[k][7] = w1[3]; }
;             float pr[6][8];
; #pragma unroll
;             for (int i = 0; i < 6; ++i) {
;                 if (t0 - 2 + i >= 0) { const size_t r2 = (size_t)(r0 - 2 + i);
;                     const v4u bw = *(const v4u*)(proj + r2 * NP + PC_SCB + c), xw = *(const v4u*)(proj + r2 * NP + PC_SCX + c);
;                     pr[i][0] = blo(bw.x) * blo(xw.x); pr[i][1] = bhi(bw.x) * bhi(xw.x); pr[i][2] = blo(bw.y) * blo(xw.y); pr[i][3] = bhi(bw.y) * bhi(xw.y);
;                     pr[i][4] = blo(bw.z) * blo(xw.z); pr[i][5] = bhi(bw.z) * bhi(xw.z); pr[i][6] = blo(bw.w) * blo(xw.w); pr[i][7] = bhi(bw.w) * bhi(xw.w);
;                 } else {
; #pragma unroll
;                     for (int j = 0; j < 8; ++j) pr[i][j] = 0.f; }
;             }
.LBB0_757:
	v_lshl_add_u64 v[8:9], s[34:35], 0, v[48:49]
	v_add_co_u32_e32 v2, vcc, 0x585a2000, v8
	s_mov_b64 s[24:25], 0x585a2c00
	s_waitcnt lgkmcnt(0)
	v_addc_co_u32_e32 v3, vcc, 0, v9, vcc
	v_lshl_add_u64 v[0:1], v[8:9], 0, s[24:25]
	s_mov_b64 s[24:25], 0x585a4c00
	v_add_co_u32_e32 v6, vcc, 0x585a4000, v8
	v_lshl_add_u64 v[4:5], v[8:9], 0, s[24:25]
	s_nop 0
	v_addc_co_u32_e32 v7, vcc, 0, v9, vcc
	s_mov_b64 s[24:25], 0x585a6c00
	v_lshl_add_u64 v[10:11], v[8:9], 0, s[24:25]
	v_add_co_u32_e32 v8, vcc, 0x585a6000, v8
	global_load_dwordx4 v[12:15], v[2:3], off offset:3072
	s_nop 0
	global_load_dwordx4 v[0:3], v[0:1], off offset:16
	v_addc_co_u32_e32 v9, vcc, 0, v9, vcc
	global_load_dwordx4 v[16:19], v[6:7], off offset:3072
	s_nop 0
	global_load_dwordx4 v[4:7], v[4:5], off offset:16
	s_nop 0
	global_load_dwordx4 v[20:23], v[8:9], off offset:3072
	s_nop 0
	global_load_dwordx4 v[8:11], v[10:11], off offset:16
	s_mov_b64 s[24:25], 0x31105000
	s_mov_b64 s[100:101], 0x31107000
	v_lshl_add_u64 v[192:193], s[34:35], 0, v[36:37]
	v_lshl_add_u64 v[198:199], v[192:193], 0, s[24:25]
	global_load_dwordx4 v[120:123], v[198:199], off
	v_lshl_add_u64 v[198:199], v[192:193], 0, s[100:101]
	global_load_dwordx4 v[124:127], v[198:199], off
	v_lshl_add_u64 v[192:193], s[34:35], 0, v[38:39]
	v_lshl_add_u64 v[198:199], v[192:193], 0, s[24:25]
	global_load_dwordx4 v[128:131], v[198:199], off
	v_lshl_add_u64 v[198:199], v[192:193], 0, s[100:101]
	global_load_dwordx4 v[132:135], v[198:199], off
	v_lshl_add_u64 v[184:185], s[34:35], 0, v[40:41]
	v_lshl_add_u64 v[198:199], v[184:185], 0, s[24:25]
	global_load_dwordx4 v[136:139], v[198:199], off
	v_lshl_add_u64 v[198:199], v[184:185], 0, s[100:101]
	global_load_dwordx4 v[140:143], v[198:199], off
	v_lshl_add_u64 v[186:187], s[34:35], 0, v[42:43]
	v_lshl_add_u64 v[198:199], v[186:187], 0, s[24:25]
	global_load_dwordx4 v[144:147], v[198:199], off
	v_lshl_add_u64 v[198:199], v[186:187], 0, s[100:101]
	global_load_dwordx4 v[148:151], v[198:199], off
	v_lshl_add_u64 v[188:189], s[34:35], 0, v[44:45]
	v_lshl_add_u64 v[198:199], v[188:189], 0, s[24:25]
	global_load_dwordx4 v[152:155], v[198:199], off
	v_lshl_add_u64 v[198:199], v[188:189], 0, s[100:101]
	global_load_dwordx4 v[156:159], v[198:199], off
	v_lshl_add_u64 v[190:191], s[34:35], 0, v[46:47]
	v_lshl_add_u64 v[198:199], v[190:191], 0, s[24:25]
	global_load_dwordx4 v[160:163], v[198:199], off
	v_lshl_add_u64 v[198:199], v[190:191], 0, s[100:101]
	global_load_dwordx4 v[164:167], v[198:199], off
	s_mov_b32 s24, s3
	s_mov_b32 s25, 0
	v_lshl_add_u64 v[198:199], v[184:185], 0, s[24:25]
	global_load_dwordx4 v[168:171], v[198:199], off
	v_lshl_add_u64 v[198:199], v[186:187], 0, s[24:25]
	global_load_dwordx4 v[172:175], v[198:199], off
	v_lshl_add_u64 v[198:199], v[188:189], 0, s[24:25]
	global_load_dwordx4 v[176:179], v[198:199], off
	v_lshl_add_u64 v[198:199], v[190:191], 0, s[24:25]
	global_load_dwordx4 v[180:183], v[198:199], off
	s_waitcnt vmcnt(0)
	v_mov_b32_e32 v56, 0
	s_andn2_b64 vcc, exec, s[30:31]
	v_mov_b32_e32 v90, 0
	v_mov_b32_e32 v91, 0
	v_mov_b32_e32 v88, 0
	v_mov_b32_e32 v89, 0
	v_mov_b32_e32 v86, 0
	v_mov_b32_e32 v87, 0
	v_mov_b32_e32 v84, 0
	v_mov_b32_e32 v85, 0
	s_cbranch_vccnz .LBB0_759
	v_lshl_add_u64 v[54:55], s[34:35], 0, v[36:37]
	v_add_co_u32_e32 v50, vcc, 0x31105000, v54
	s_nop 1
	v_addc_co_u32_e32 v51, vcc, 0, v55, vcc
	v_add_co_u32_e32 v54, vcc, 0x31107000, v54
	v_mov_b32_e32 v50, v120
	v_mov_b32_e32 v51, v121
	v_mov_b32_e32 v52, v122
	v_mov_b32_e32 v53, v123
	s_nop 0
	v_addc_co_u32_e32 v55, vcc, 0, v55, vcc
	v_mov_b32_e32 v58, v124
	v_mov_b32_e32 v59, v125
	v_mov_b32_e32 v60, v126
	v_mov_b32_e32 v61, v127
	s_waitcnt vmcnt(1)
	v_lshlrev_b32_e32 v54, 16, v50
	v_and_b32_e32 v55, 0xffff0000, v50
	v_lshlrev_b32_e32 v50, 16, v51
	s_waitcnt vmcnt(0)
	v_lshlrev_b32_e32 v62, 16, v58
	v_and_b32_e32 v63, 0xffff0000, v58
	v_pk_mul_f32 v[84:85], v[54:55], v[62:63]
	v_and_b32_e32 v51, 0xffff0000, v51
	v_lshlrev_b32_e32 v54, 16, v59
	v_and_b32_e32 v55, 0xffff0000, v59
	v_pk_mul_f32 v[86:87], v[50:51], v[54:55]
	v_lshlrev_b32_e32 v50, 16, v52
	v_and_b32_e32 v51, 0xffff0000, v52
	v_lshlrev_b32_e32 v54, 16, v60
	v_and_b32_e32 v55, 0xffff0000, v60
	v_pk_mul_f32 v[88:89], v[50:51], v[54:55]
	v_lshlrev_b32_e32 v50, 16, v53
	v_and_b32_e32 v51, 0xffff0000, v53
	v_lshlrev_b32_e32 v52, 16, v61
	v_and_b32_e32 v53, 0xffff0000, v61
	v_pk_mul_f32 v[90:91], v[50:51], v[52:53]
.LBB0_759:
	s_andn2_b64 vcc, exec, s[48:49]
	v_mov_b32_e32 v57, 0
	v_mov_b32_e32 v68, 0
	v_mov_b32_e32 v69, 0
	v_mov_b32_e32 v72, 0
	v_mov_b32_e32 v73, 0
	v_mov_b32_e32 v78, 0
	v_mov_b32_e32 v79, 0
	s_cbranch_vccnz .LBB0_761
	v_lshl_add_u64 v[54:55], s[34:35], 0, v[38:39]
	v_add_co_u32_e32 v50, vcc, 0x31105000, v54
	s_nop 1
	v_addc_co_u32_e32 v51, vcc, 0, v55, vcc
	v_add_co_u32_e32 v54, vcc, 0x31107000, v54
	v_mov_b32_e32 v50, v128
	v_mov_b32_e32 v51, v129
	v_mov_b32_e32 v52, v130
	v_mov_b32_e32 v53, v131
	s_nop 0
	v_addc_co_u32_e32 v55, vcc, 0, v55, vcc
	v_mov_b32_e32 v54, v132
	v_mov_b32_e32 v55, v133
	v_mov_b32_e32 v56, v134
	v_mov_b32_e32 v57, v135
	s_waitcnt vmcnt(1)
	v_lshlrev_b32_e32 v58, 16, v50
	v_and_b32_e32 v59, 0xffff0000, v50
	v_lshlrev_b32_e32 v50, 16, v51
	s_waitcnt vmcnt(0)
	v_lshlrev_b32_e32 v60, 16, v54
	v_and_b32_e32 v61, 0xffff0000, v54
	v_and_b32_e32 v51, 0xffff0000, v51
	v_lshlrev_b32_e32 v54, 16, v55
	v_and_b32_e32 v55, 0xffff0000, v55
	v_pk_mul_f32 v[72:73], v[50:51], v[54:55]
	v_lshlrev_b32_e32 v50, 16, v52
	v_and_b32_e32 v51, 0xffff0000, v52
	v_lshlrev_b32_e32 v54, 16, v56
	v_and_b32_e32 v55, 0xffff0000, v56
	v_pk_mul_f32 v[68:69], v[50:51], v[54:55]
	v_lshlrev_b32_e32 v50, 16, v53
	v_and_b32_e32 v51, 0xffff0000, v53
	v_lshlrev_b32_e32 v52, 16, v57
	v_and_b32_e32 v53, 0xffff0000, v57
	v_pk_mul_f32 v[78:79], v[58:59], v[60:61]
	v_pk_mul_f32 v[56:57], v[50:51], v[52:53]
; __device__ __forceinline__ float blo(unsigned w) { return __uint_as_float(w << 16); }
; __device__ __forceinline__ float bhi(unsigned w) { return __uint_as_float(w & 0xffff0000u); }
; __device__ __forceinline__ void n2_phase(unsigned char* ws, int layer, int gw, int NGW, int lane) {
;     ...
;             for (int i = 0; i < 6; ++i) {
;                 if (t0 - 2 + i >= 0) { const size_t r2 = (size_t)(r0 - 2 + i);
;                     const v4u bw = *(const v4u*)(proj + r2 * NP + PC_SCB + c), xw = *(const v4u*)(proj + r2 * NP + PC_SCX + c);
;                     pr[i][0] = blo(bw.x) * blo(xw.x); pr[i][1] = bhi(bw.x) * bhi(xw.x); pr[i][2] = blo(bw.y) * blo(xw.y); pr[i][3] = bhi(bw.y) * bhi(xw.y);
;                     pr[i][4] = blo(bw.z) * blo(xw.z); pr[i][5] = bhi(bw.z) * bhi(xw.z); pr[i][6] = blo(bw.w) * blo(xw.w); pr[i][7] = bhi(bw.w) * bhi(xw.w);
;                 } else {
; #pragma unroll
;                     for (int j = 0; j < 8; ++j) pr[i][j] = 0.f; }
;             }
.LBB0_761:
	v_mov_b32_e32 v50, 0
	s_andn2_b64 vcc, exec, s[52:53]
	v_lshl_add_u64 v[104:105], s[34:35], 0, v[40:41]
	v_mov_b32_e32 v64, 0
	v_mov_b32_e32 v65, 0
	v_mov_b32_e32 v60, 0
	v_mov_b32_e32 v61, 0
	v_mov_b32_e32 v62, 0
	v_mov_b32_e32 v63, 0
	v_mov_b32_e32 v66, 0
	v_mov_b32_e32 v67, 0
	s_cbranch_vccnz .LBB0_763
	v_add_co_u32_e32 v52, vcc, 0x31105000, v104
	s_nop 1
	v_addc_co_u32_e32 v53, vcc, 0, v105, vcc
	v_add_co_u32_e32 v58, vcc, 0x31107000, v104
	v_mov_b32_e32 v52, v136
	v_mov_b32_e32 v53, v137
	v_mov_b32_e32 v54, v138
	v_mov_b32_e32 v55, v139
	s_nop 0
	v_addc_co_u32_e32 v59, vcc, 0, v105, vcc
	v_mov_b32_e32 v62, v140
	v_mov_b32_e32 v63, v141
	v_mov_b32_e32 v64, v142
	v_mov_b32_e32 v65, v143
	s_waitcnt vmcnt(1)
	v_lshlrev_b32_e32 v58, 16, v52
	v_and_b32_e32 v59, 0xffff0000, v52
	v_lshlrev_b32_e32 v52, 16, v53
	s_waitcnt vmcnt(0)
	v_lshlrev_b32_e32 v60, 16, v62
	v_and_b32_e32 v61, 0xffff0000, v62
	v_pk_mul_f32 v[66:67], v[58:59], v[60:61]
	v_and_b32_e32 v53, 0xffff0000, v53
	v_lshlrev_b32_e32 v58, 16, v63
	v_and_b32_e32 v59, 0xffff0000, v63
	v_pk_mul_f32 v[62:63], v[52:53], v[58:59]
	v_lshlrev_b32_e32 v52, 16, v54
	v_and_b32_e32 v53, 0xffff0000, v54
	v_lshlrev_b32_e32 v58, 16, v64
	v_and_b32_e32 v59, 0xffff0000, v64
	v_pk_mul_f32 v[60:61], v[52:53], v[58:59]
	v_lshlrev_b32_e32 v52, 16, v55
	v_and_b32_e32 v53, 0xffff0000, v55
	v_lshlrev_b32_e32 v54, 16, v65
	v_and_b32_e32 v55, 0xffff0000, v65
	v_pk_mul_f32 v[64:65], v[52:53], v[54:55]
.LBB0_763:
	s_andn2_b64 vcc, exec, s[56:57]
	v_lshl_add_u64 v[102:103], s[34:35], 0, v[42:43]
	v_mov_b32_e32 v51, 0
	v_mov_b32_e32 v52, 0
	v_mov_b32_e32 v53, 0
	v_mov_b32_e32 v54, 0
	v_mov_b32_e32 v55, 0
	v_mov_b32_e32 v58, 0
	v_mov_b32_e32 v59, 0
	s_cbranch_vccnz .LBB0_765
	v_add_co_u32_e32 v50, vcc, 0x31105000, v102
	s_nop 1
	v_addc_co_u32_e32 v51, vcc, 0, v103, vcc
	v_mov_b32_e32 v74, v144
	v_mov_b32_e32 v75, v145
	v_mov_b32_e32 v76, v146
	v_mov_b32_e32 v77, v147
	v_add_co_u32_e32 v50, vcc, 0x31107000, v102
	s_nop 1
	v_addc_co_u32_e32 v51, vcc, 0, v103, vcc
	v_mov_b32_e32 v80, v148
	v_mov_b32_e32 v81, v149
	v_mov_b32_e32 v82, v150
	v_mov_b32_e32 v83, v151
	s_waitcnt vmcnt(1)
	v_lshlrev_b32_e32 v50, 16, v74
	v_and_b32_e32 v51, 0xffff0000, v74
	s_waitcnt vmcnt(0)
	v_lshlrev_b32_e32 v52, 16, v80
	v_and_b32_e32 v53, 0xffff0000, v80
	v_pk_mul_f32 v[58:59], v[50:51], v[52:53]
	v_lshlrev_b32_e32 v50, 16, v75
	v_and_b32_e32 v51, 0xffff0000, v75
	v_lshlrev_b32_e32 v52, 16, v81
	v_and_b32_e32 v53, 0xffff0000, v81
	v_pk_mul_f32 v[54:55], v[50:51], v[52:53]
	v_lshlrev_b32_e32 v50, 16, v76
	v_and_b32_e32 v51, 0xffff0000, v76
	v_lshlrev_b32_e32 v52, 16, v82
	v_and_b32_e32 v53, 0xffff0000, v82
	v_pk_mul_f32 v[52:53], v[50:51], v[52:53]
	v_lshlrev_b32_e32 v50, 16, v77
	v_and_b32_e32 v51, 0xffff0000, v77
	v_lshlrev_b32_e32 v70, 16, v83
	v_and_b32_e32 v71, 0xffff0000, v83
	v_pk_mul_f32 v[50:51], v[50:51], v[70:71]
.LBB0_765:
	v_mov_b32_e32 v80, 0
	s_andn2_b64 vcc, exec, s[58:59]
	v_lshl_add_u64 v[100:101], s[34:35], 0, v[44:45]
	v_mov_b32_e32 v76, 0
	v_mov_b32_e32 v77, 0
	v_mov_b32_e32 v70, 0
	v_mov_b32_e32 v71, 0
	v_mov_b32_e32 v74, 0
	v_mov_b32_e32 v75, 0
	v_mov_b32_e32 v82, 0
	v_mov_b32_e32 v83, 0
	s_cbranch_vccnz .LBB0_767
	v_add_co_u32_e32 v70, vcc, 0x31105000, v100
	s_nop 1
	v_addc_co_u32_e32 v71, vcc, 0, v101, vcc
	v_mov_b32_e32 v74, v152
	v_mov_b32_e32 v75, v153
	v_mov_b32_e32 v76, v154
	v_mov_b32_e32 v77, v155
	v_add_co_u32_e32 v70, vcc, 0x31107000, v100
	s_nop 1
	v_addc_co_u32_e32 v71, vcc, 0, v101, vcc
	v_mov_b32_e32 v92, v156
	v_mov_b32_e32 v93, v157
	v_mov_b32_e32 v94, v158
	v_mov_b32_e32 v95, v159
	s_waitcnt vmcnt(1)
	v_lshlrev_b32_e32 v70, 16, v74
	v_and_b32_e32 v71, 0xffff0000, v74
	s_waitcnt vmcnt(0)
	v_lshlrev_b32_e32 v82, 16, v92
	v_and_b32_e32 v83, 0xffff0000, v92
	v_pk_mul_f32 v[82:83], v[70:71], v[82:83]
	v_lshlrev_b32_e32 v70, 16, v75
	v_and_b32_e32 v71, 0xffff0000, v75
	v_lshlrev_b32_e32 v74, 16, v93
	v_and_b32_e32 v75, 0xffff0000, v93
	v_pk_mul_f32 v[74:75], v[70:71], v[74:75]
	v_lshlrev_b32_e32 v70, 16, v76
	v_and_b32_e32 v71, 0xffff0000, v76
	v_lshlrev_b32_e32 v92, 16, v94
	v_and_b32_e32 v93, 0xffff0000, v94
	v_pk_mul_f32 v[70:71], v[70:71], v[92:93]
	v_lshlrev_b32_e32 v76, 16, v77
	v_and_b32_e32 v77, 0xffff0000, v77
	v_lshlrev_b32_e32 v92, 16, v95
	v_and_b32_e32 v93, 0xffff0000, v95
	v_pk_mul_f32 v[76:77], v[76:77], v[92:93]
.LBB0_767:
	s_andn2_b64 vcc, exec, s[64:65]
	v_lshl_add_u64 v[94:95], s[34:35], 0, v[46:47]
	v_mov_b32_e32 v81, 0
	v_mov_b32_e32 v92, 0
	v_mov_b32_e32 v93, 0
	v_mov_b32_e32 v96, 0
	v_mov_b32_e32 v97, 0
	v_mov_b32_e32 v98, 0
	v_mov_b32_e32 v99, 0
	s_cbranch_vccnz .LBB0_756
	v_add_co_u32_e32 v80, vcc, 0x31105000, v94
	s_nop 1
	v_addc_co_u32_e32 v81, vcc, 0, v95, vcc
	v_mov_b32_e32 v96, v160
	v_mov_b32_e32 v97, v161
	v_mov_b32_e32 v98, v162
	v_mov_b32_e32 v99, v163
	v_add_co_u32_e32 v80, vcc, 0x31107000, v94
	s_nop 1
	v_addc_co_u32_e32 v81, vcc, 0, v95, vcc
	v_mov_b32_e32 v110, v164
	v_mov_b32_e32 v111, v165
	v_mov_b32_e32 v112, v166
	v_mov_b32_e32 v113, v167
	s_waitcnt vmcnt(1)
	v_and_b32_e32 v80, 0xffff0000, v96
	v_lshlrev_b32_e32 v81, 16, v96
	s_waitcnt vmcnt(0)
	v_and_b32_e32 v92, 0xffff0000, v110
	v_lshlrev_b32_e32 v93, 16, v110
	v_pk_mul_f32 v[114:115], v[80:81], v[92:93]
	v_and_b32_e32 v80, 0xffff0000, v97
	v_lshlrev_b32_e32 v81, 16, v97
	v_and_b32_e32 v92, 0xffff0000, v111
	v_lshlrev_b32_e32 v93, 16, v111
	v_pk_mul_f32 v[110:111], v[80:81], v[92:93]
	v_and_b32_e32 v80, 0xffff0000, v98
	v_lshlrev_b32_e32 v81, 16, v98
	v_and_b32_e32 v92, 0xffff0000, v112
	v_lshlrev_b32_e32 v93, 16, v112
	v_pk_mul_f32 v[96:97], v[80:81], v[92:93]
	v_and_b32_e32 v80, 0xffff0000, v99
	v_lshlrev_b32_e32 v81, 16, v99
	v_and_b32_e32 v92, 0xffff0000, v113
	v_lshlrev_b32_e32 v93, 16, v113
	v_pk_mul_f32 v[92:93], v[80:81], v[92:93]
	v_mov_b32_e32 v98, v115
	v_mov_b32_e32 v80, v93
	v_mov_b32_e32 v81, v92
	v_mov_b32_e32 v92, v97
	v_mov_b32_e32 v93, v96
	v_mov_b32_e32 v96, v111
	v_mov_b32_e32 v97, v110
	v_mov_b32_e32 v99, v114
	s_branch .LBB0_756
